# final-norm gains loaded once; compress-MLP loop loads issued up front with counted waits; sel task q loads paired
# baseline (speedup 1.0000x reference)
; __device__ __forceinline__ unsigned cvt_pk_bf16(float lo, float hi) { f32x2 v = {lo, hi}; bf16x2_t b = __builtin_convertvector(v, bf16x2_t); return __builtin_bit_cast(unsigned, b); }
; __device__ __forceinline__ float bflo(unsigned w) { return __uint_as_float(w << 16); }
; __device__ __forceinline__ float bfhi(unsigned w) { return __uint_as_float(w & 0xffff0000u); }
; #define LBAR() asm volatile("s_waitcnt lgkmcnt(0)\n\ts_barrier" ::: "memory")
; __device__ __forceinline__ f32x4 mfma16(bf16x8 a, bf16x8 b, f32x4 c) { return __builtin_amdgcn_mfma_f32_16x16x32_bf16(a, b, c, 0, 0, 0); }
;   __device__ __forceinline__ bf16_t* PROJ() const { return (bf16_t*)(ws + WS_PROJ); }
; __device__ __forceinline__ void nsa_compress_task(LAS unsigned char* lds, const Ctx& X, const float* pe_k, const float* pe_v, int task) {
;     ...
; #pragma unroll 2
;   for (int k8 = 0; k8 < 8; ++k8) { const int kk = 8 * w + k8; const int lt = kk >> 1, d = (kk & 1) * 32 + 8 * lg;
;     int tok = 16 * cmy + lt; tok = tok > S - 1 ? S - 1 : tok;
;     const u32x4 kv = *(const u32x4*)(X.PROJ() + ((size_t)b * S + tok) * NPROJ + col + d);
;     const f32x4 pa = *(const f32x4*)(pe + lt * 64 + d), pb = *(const f32x4*)(pe + lt * 64 + d + 4);
;     u32x4 aw; aw.x = cvt_pk_bf16(bflo(kv.x) + pa[0], bfhi(kv.x) + pa[1]); aw.y = cvt_pk_bf16(bflo(kv.y) + pa[2], bfhi(kv.y) + pa[3]);
;     aw.z = cvt_pk_bf16(bflo(kv.z) + pb[0], bfhi(kv.z) + pb[1]); aw.w = cvt_pk_bf16(bflo(kv.w) + pb[2], bfhi(kv.w) + pb[3]);
;     const bf16x8 af = __builtin_bit_cast(bf16x8, aw);
; #pragma unroll
;     for (int nt = 0; nt < 4; ++nt) { const bf16x8 bfr = *(const bf16x8*)(w1 + (size_t)(16 * nt + r) * 2048 + 32 * kk + 8 * lg); acc[nt] = mfma16(af, bfr, acc[nt]); }
;   }
; #pragma unroll
;   for (int nt = 0; nt < 4; ++nt)
; #pragma unroll
;     for (int i = 0; i < 4; ++i) red[(w * 16 + 4 * lg + i) * 64 + 16 * nt + r] = acc[nt][i];
;   LBAR();
.LBB0_529:
	s_ashr_i32 s8, s17, 1
	v_add_u32_e32 v28, s8, v37
	v_min_i32_e32 v28, 0x1fff, v28
	v_ashrrev_i32_e32 v29, 31, v28
	v_lshl_add_u64 v[28:29], v[28:29], 0, s[40:41]
	v_mad_u64_u32 v[30:31], s[8:9], v28, s82, v[20:21]
	v_mad_i32_i24 v31, v29, s82, v31
	v_lshl_add_u64 v[46:47], v[24:25], 0, s[14:15]
	s_mov_b32 s9, 0
	s_mov_b32 s8, 0x1400000
	v_lshl_add_u64 v[92:93], v[46:47], 0, s[8:9]
	global_load_dwordx4 v[60:63], v[92:93], off
	global_load_dwordx4 v[76:79], v[92:93], off offset:64
	s_mov_b32 s8, 0x1410000
	v_lshl_add_u64 v[92:93], v[46:47], 0, s[8:9]
	global_load_dwordx4 v[64:67], v[92:93], off
	global_load_dwordx4 v[80:83], v[92:93], off offset:64
	s_mov_b32 s8, 0x1420000
	v_lshl_add_u64 v[92:93], v[46:47], 0, s[8:9]
	global_load_dwordx4 v[68:71], v[92:93], off
	global_load_dwordx4 v[84:87], v[92:93], off offset:64
	s_mov_b32 s8, 0x1430000
	v_lshl_add_u64 v[92:93], v[46:47], 0, s[8:9]
	global_load_dwordx4 v[72:75], v[92:93], off
	global_load_dwordx4 v[88:91], v[92:93], off offset:64
	global_load_dwordx4 v[28:31], v[30:31], off
	global_load_dwordx4 v[32:35], v[26:27], off
	global_load_dwordx4 v[38:41], v[26:27], off offset:-16
	s_add_i32 s8, s17, 1
	s_ashr_i32 s29, s8, 1
	v_add_u32_e32 v94, s29, v37
	v_min_i32_e32 v94, 0x1fff, v94
	v_ashrrev_i32_e32 v95, 31, v94
	v_lshl_add_u64 v[94:95], v[94:95], 0, s[40:41]
	v_mad_u64_u32 v[96:97], s[8:9], v94, s82, v[20:21]
	s_lshl_b32 s8, s29, 6
	v_mad_i32_i24 v97, v95, s82, v97
	s_ashr_i32 s9, s8, 31
	global_load_dwordx4 v[100:103], v[96:97], off offset:64
	v_lshl_add_u64 v[98:99], s[8:9], 2, v[22:23]
	global_load_dwordx4 v[104:107], v[98:99], off offset:144
	global_load_dwordx4 v[108:111], v[98:99], off offset:128
	v_lshl_add_u64 v[26:27], v[26:27], 0, s[62:63]
	s_add_u32 s14, s14, 0x80
	s_addc_u32 s15, s15, 0
	s_add_i32 s17, s17, 2
	s_waitcnt vmcnt(5)
	v_lshlrev_b32_e32 v42, 16, v28
	v_and_b32_e32 v43, 0xffff0000, v28
	v_lshlrev_b32_e32 v28, 16, v29
	v_and_b32_e32 v29, 0xffff0000, v29
	s_waitcnt vmcnt(3)
	v_pk_add_f32 v[38:39], v[38:39], v[42:43]
	v_pk_add_f32 v[28:29], v[40:41], v[28:29]
	v_cvt_pk_bf16_f32 v38, v38, v39
	v_cvt_pk_bf16_f32 v39, v28, v29
	v_lshlrev_b32_e32 v28, 16, v30
	v_and_b32_e32 v29, 0xffff0000, v30
	v_pk_add_f32 v[28:29], v[32:33], v[28:29]
	s_nop 0
	v_cvt_pk_bf16_f32 v40, v28, v29
	v_lshlrev_b32_e32 v28, 16, v31
	v_and_b32_e32 v29, 0xffff0000, v31
	v_pk_add_f32 v[28:29], v[34:35], v[28:29]
	s_nop 0
	v_cvt_pk_bf16_f32 v41, v28, v29
	s_nop 1
	v_mfma_f32_16x16x32_bf16 v[2:5], v[38:41], v[60:63], v[2:5]
	v_mfma_f32_16x16x32_bf16 v[10:13], v[38:41], v[64:67], v[10:13]
	v_mfma_f32_16x16x32_bf16 v[14:17], v[38:41], v[68:71], v[14:17]
	v_mfma_f32_16x16x32_bf16 v[6:9], v[38:41], v[72:75], v[6:9]
	s_waitcnt vmcnt(2)
	v_lshlrev_b32_e32 v116, 16, v100
	v_and_b32_e32 v117, 0xffff0000, v100
	s_waitcnt vmcnt(0)
	v_pk_add_f32 v[118:119], v[108:109], v[116:117]
	s_nop 0
	v_cvt_pk_bf16_f32 v112, v118, v119
	v_lshlrev_b32_e32 v116, 16, v101
	v_and_b32_e32 v117, 0xffff0000, v101
	v_pk_add_f32 v[118:119], v[110:111], v[116:117]
	s_nop 0
	v_cvt_pk_bf16_f32 v113, v118, v119
	v_lshlrev_b32_e32 v116, 16, v102
	v_and_b32_e32 v117, 0xffff0000, v102
	v_pk_add_f32 v[118:119], v[104:105], v[116:117]
	s_nop 0
	v_cvt_pk_bf16_f32 v114, v118, v119
	v_lshlrev_b32_e32 v116, 16, v103
	v_and_b32_e32 v117, 0xffff0000, v103
	v_pk_add_f32 v[118:119], v[106:107], v[116:117]
	s_nop 0
	v_cvt_pk_bf16_f32 v115, v118, v119
	s_nop 1
	v_mfma_f32_16x16x32_bf16 v[2:5], v[112:115], v[76:79], v[2:5]
	v_mfma_f32_16x16x32_bf16 v[10:13], v[112:115], v[80:83], v[10:13]
	v_mfma_f32_16x16x32_bf16 v[14:17], v[112:115], v[84:87], v[14:17]
	v_mfma_f32_16x16x32_bf16 v[6:9], v[112:115], v[88:91], v[6:9]
	s_cmpk_eq_i32 s14, 0x200
	s_cbranch_scc0 .LBB0_529
	v_lshlrev_b32_e32 v20, 10, v1
	v_lshl_or_b32 v21, s16, 12, v20
	v_lshl_add_u32 v20, v19, 2, 0
	v_add_u32_e32 v21, v20, v21
	s_nop 0
	ds_write2_b32 v21, v2, v10 offset1:16
	ds_write2_b32 v21, v3, v11 offset0:64 offset1:80
	ds_write2_b32 v21, v4, v12 offset0:128 offset1:144
	ds_write2_b32 v21, v5, v13 offset0:192 offset1:208
	ds_write2_b32 v21, v14, v6 offset0:32 offset1:48
	ds_write2_b32 v21, v15, v7 offset0:96 offset1:112
	ds_write2_b32 v21, v16, v8 offset0:160 offset1:176
	ds_write2_b32 v21, v17, v9 offset0:224 offset1:240
	s_waitcnt lgkmcnt(0)
	s_barrier
	v_cmp_gt_i32_e32 vcc, s93, v36
	s_and_saveexec_b64 s[14:15], vcc
	s_cbranch_execz .LBB0_533
	v_and_b32_e32 v2, 63, v36
	v_lshl_add_u32 v2, v2, 1, 0
	v_lshl_add_u32 v3, v36, 2, 0
	s_mov_b64 s[16:17], 0

; __device__ __forceinline__ void nsa_sel_phase(const Ctx& X, bf16_t* OBp) {
;     ...
;   for (; k < ntask; k += npw) {
;     ...
;     sl = sln;
.LBB0_1342:
	s_or_b64 exec, exec, s[26:27]
	v_mov_b64_e32 v[72:73], v[56:57]
	s_andn2_b64 vcc, exec, s[20:21]
	s_mov_b32 s8, s53
	v_mov_b64_e32 v[70:71], v[54:55]
	s_cbranch_vccz .LBB0_1363

; __device__ __forceinline__ float bflo(unsigned w) { return __uint_as_float(w << 16); }
; __device__ __forceinline__ float bfhi(unsigned w) { return __uint_as_float(w & 0xffff0000u); }
; __device__ __forceinline__ long as_long(unsigned lo, unsigned hi) { return (long)(((unsigned long long)hi << 32) | (unsigned long long)lo); }
;   __device__ __forceinline__ bf16_t* QROT() const { return (bf16_t*)(ws + WS_QROT); }
;   __device__ __forceinline__ bf16_t* VST() const { return (bf16_t*)(ws + WS_VST); }
;   __device__ __forceinline__ bf16_t* KST() const { return (bf16_t*)(ws + WS_KST); }
; __device__ __forceinline__ void nsa_sel_phase(const Ctx& X, bf16_t* OBp) {
;     ...
;   { int b, g, t; SEL_DECODE(k, b, g, t); sl = *(const u32x4*)(X.SELL() + (((size_t)b * S + t) * 2 + g) * 16); sln = sl;
;     sel_load(FA, (const bf16_t*)((const unsigned char*)X.KST() + (size_t)(b * 2 + g) * 128 * 4096), (const bf16_t*)((const unsigned char*)X.VST() + (size_t)(b * 2 + g) * 128 * 4096), sel_slot(sl, 0), cq, lg); }
;   for (; k < ntask; k += npw) {
;     int b, g, t; SEL_DECODE(k, b, g, t);
;     const int cur = t >> 6; const int nv = cur + 1 < 16 ? cur + 1 : 16;
;     const size_t rowbase = (size_t)b * S, row = rowbase + t;
;     const bf16_t* projk = (const bf16_t*)((const unsigned char*)X.KST() + (size_t)(b * 2 + g) * 128 * 4096);
;     const bf16_t* vst = (const bf16_t*)((const unsigned char*)X.VST() + (size_t)(b * 2 + g) * 128 * 4096);
;     const int kn = k + npw; int bn = b, gn = g, tn = t;
;     if (kn < ntask) { SEL_DECODE(kn, bn, gn, tn); sln = *(const u32x4*)(X.SELL() + (((size_t)bn * S + tn) * 2 + gn) * 16); }
;     long qs[2];
; #pragma unroll
;     for (int kk = 0; kk < 2; ++kk) { const u32x4 qw4 = *(const u32x4*)(X.QROT() + row * 512 + 64 * (4 * g + hcol) + 32 * kk + 8 * lg);
;       const float a4[4] = {bflo(qw4.x), bfhi(qw4.x), bflo(qw4.y), bfhi(qw4.y)}, b4[4] = {bflo(qw4.z), bfhi(qw4.z), bflo(qw4.w), bfhi(qw4.w)};
;       const u32x2 q8 = pack8_fp8(a4, b4); qs[kk] = as_long(q8.x, q8.y); }
;     float m = -INFINITY, l = 0.f; f32x4 os[4];
; #pragma unroll
;     for (int dt = 0; dt < 4; ++dt) os[dt] = (f32x4){0.f, 0.f, 0.f, 0.f};
;     int blkA = sel_slot(sl, 0), blkB = 0;
.LBB0_1345:
	s_bfe_u32 s9, s8, 0xd0001
	s_and_b64 s[22:23], s[94:95], exec
	s_cselect_b32 s29, s8, s9
	s_ashr_i32 s39, s38, 31
	s_ashr_i32 s59, s29, 6
	s_lshl_b64 s[8:9], s[38:39], 13
	s_ashr_i32 s22, s29, 31
	s_add_u32 s24, s8, s29
	s_addc_u32 s25, s9, s22
	s_lshl_b64 s[22:23], s[24:25], 10
	v_readfirstlane_b32 s8, v70
	s_cmp_lt_i32 s59, 0
	v_mov_b32_e32 v89, 0
	s_cbranch_scc1 .LBB0_1358
	s_lshl_b32 s9, s38, 1
	s_or_b32 s38, s9, s58
	s_ashr_i32 s39, s38, 31
	s_lshl_b64 s[38:39], s[38:39], 19
	s_add_u32 s46, s45, s22
	s_addc_u32 s47, s52, s23
	v_lshl_or_b32 v74, s58, 9, v108
	v_mov_b32_e32 v75, v0
	v_lshl_add_u64 v[74:75], s[46:47], 0, v[74:75]
	v_mov_b32_e32 v99, v0
	v_lshl_add_u64 v[78:79], v[74:75], 0, v[98:99]
	global_load_dwordx4 v[74:77], v[78:79], off
	global_load_dwordx4 v[140:143], v[78:79], off offset:64
	v_mov_b32_e32 v100, v0
	v_mov_b32_e32 v101, v0
	v_mov_b32_e32 v102, v0
	v_mov_b32_e32 v103, v0
	v_mov_b32_e32 v99, 0
	v_lshl_add_u64 v[104:105], v[94:95], 0, s[38:39]
	v_lshl_add_u64 v[106:107], v[96:97], 0, s[38:39]
	s_min_i32 s64, s59, 15
	s_and_b32 s65, s8, 0x7f
	v_mov_b32_e32 v109, 0xff800000
	s_mov_b32 s68, 0
	s_mov_b32 s70, 0
	s_mov_b32 s69, 0
	v_mov_b32_e32 v84, v99
	v_mov_b32_e32 v85, v99
	v_mov_b32_e32 v86, v99
	v_mov_b32_e32 v87, v99
	v_mov_b32_e32 v88, v99
	v_mov_b32_e32 v89, v99
	s_waitcnt vmcnt(0)
	v_lshlrev_b32_e32 v80, 16, v74
	v_and_b32_e32 v74, 0xffff0000, v74
	v_lshlrev_b32_e32 v82, 16, v76
	v_and_b32_e32 v76, 0xffff0000, v76
	v_cvt_pk_fp8_f32 v100, v80, v74
	v_cvt_pk_fp8_f32 v101, v82, v76
	v_lshlrev_b32_e32 v81, 16, v75
	v_and_b32_e32 v75, 0xffff0000, v75
	v_lshlrev_b32_e32 v83, 16, v77
	v_and_b32_e32 v77, 0xffff0000, v77
	v_cvt_pk_fp8_f32 v100, v81, v75 op_sel:[0,0,1]
	v_cvt_pk_fp8_f32 v101, v83, v77 op_sel:[0,0,1]
	v_mov_b32_e32 v74, v140
	v_mov_b32_e32 v75, v141
	v_mov_b32_e32 v76, v142
	v_mov_b32_e32 v77, v143
	v_mov_b32_e32 v82, 0
	v_mov_b32_e32 v83, v99
	v_lshlrev_b32_e32 v78, 16, v74
	v_and_b32_e32 v74, 0xffff0000, v74
	v_lshlrev_b32_e32 v80, 16, v76
	v_and_b32_e32 v76, 0xffff0000, v76
	v_cvt_pk_fp8_f32 v102, v78, v74
	v_cvt_pk_fp8_f32 v103, v80, v76
	v_lshlrev_b32_e32 v79, 16, v75
	v_and_b32_e32 v75, 0xffff0000, v75
	v_lshlrev_b32_e32 v81, 16, v77
	v_and_b32_e32 v77, 0xffff0000, v77
	v_cvt_pk_fp8_f32 v102, v79, v75 op_sel:[0,0,1]
	v_cvt_pk_fp8_f32 v103, v81, v77 op_sel:[0,0,1]
	v_mov_b32_e32 v78, v99
	v_mov_b32_e32 v79, v99
	v_mov_b32_e32 v80, v99
	v_mov_b32_e32 v81, v99
	v_mov_b32_e32 v74, v99
	v_mov_b32_e32 v75, v99
	v_mov_b32_e32 v76, v99
	v_mov_b32_e32 v77, v99
	s_cmp_lt_i32 s70, s64
	s_cselect_b64 s[38:39], -1, 0
	s_cmp_ge_i32 s70, s64
	s_cbranch_scc1 .Lsel_a0

; __device__ __forceinline__ int otid() { int t = threadIdx.x; asm volatile("" : "+v"(t)); return t; }
; __device__ __forceinline__ void final_norm_phase(const Ctx& X, const float* gain) {
;   const int tid_ = otid(); const int lane = tid_ & 63, gw = X.blk * 8 + (tid_ >> 6), NGW = X.G * 8;
;   for (int mrow = gw; mrow < T; mrow += NGW) {
;     f32x4* xr = (f32x4*)(X.out + (size_t)mrow * 1024) + lane; const f32x4* gr = (const f32x4*)gain + lane;
;     f32x4 v[4]; float s = 0.f;
; #pragma unroll
;     for (int j = 0; j < 4; ++j) { v[j] = xr[64 * j]; s += (v[j].x * v[j].x + v[j].y * v[j].y) + (v[j].z * v[j].z + v[j].w * v[j].w); }
;     const float rstd = 1.0f / sqrtf(wave_sum(s) * (1.f / 1024.f) + NORM_EPS);
; #pragma unroll
;     for (int j = 0; j < 4; ++j) { const f32x4 gg = gr[64 * j]; xr[64 * j] = (f32x4){v[j].x * rstd * gg.x, v[j].y * rstd * gg.y, v[j].z * rstd * gg.z, v[j].w * rstd * gg.w}; }
;   }
; }
.LBB0_2129:
	s_mov_b64 s[4:5], 0
	s_mov_b32 s6, 28
	v_readlane_b32 s12, v254, 20
	v_ashrrev_i32_e32 v2, 6, v226
	s_mov_b32 s7, 0x8000
	v_add_u32_e32 v4, s12, v2
	s_mov_b64 s[2:3], 0
	v_readlane_b32 s13, v254, 21
	v_cmp_gt_i32_e32 vcc, s7, v4
	s_and_saveexec_b64 s[8:9], vcc
	s_cbranch_execz .LBB0_2132
	v_and_b32_e32 v3, 64, v233
	v_add_u32_e32 v3, 64, v3
	v_xor_b32_e32 v5, 1, v233
	v_cmp_lt_i32_e32 vcc, v5, v3
	v_xor_b32_e32 v6, 2, v233
	v_xor_b32_e32 v7, 4, v233
	v_cndmask_b32_e32 v5, v233, v5, vcc
	v_cmp_lt_i32_e32 vcc, v6, v3
	v_xor_b32_e32 v8, 8, v233
	s_ashr_i32 s7, s6, 31
	v_cndmask_b32_e32 v6, v233, v6, vcc
	v_cmp_lt_i32_e32 vcc, v7, v3
	v_xor_b32_e32 v9, 16, v233
	s_lshl_b64 s[6:7], s[6:7], 3
	v_cndmask_b32_e32 v7, v233, v7, vcc
	v_cmp_lt_i32_e32 vcc, v8, v3
	v_xor_b32_e32 v10, 32, v233
	s_add_u32 s6, s0, s6
	v_cndmask_b32_e32 v8, v233, v8, vcc
	v_cmp_lt_i32_e32 vcc, v9, v3
	s_addc_u32 s7, s1, s7
	s_load_dwordx2 s[8:9], s[6:7], 0x0
	s_load_dwordx2 s[10:11], s[0:1], 0xe8
	v_cndmask_b32_e32 v9, v233, v9, vcc
	v_cmp_lt_i32_e32 vcc, v10, v3
	v_and_b32_e32 v0, 63, v226
	v_mov_b32_e32 v13, 0
	v_cndmask_b32_e32 v3, v233, v10, vcc
	v_lshlrev_b32_e32 v10, 2, v3
	v_ashrrev_i32_e32 v3, 31, v2
	v_lshl_add_u64 v[2:3], v[2:3], 0, s[12:13]
	v_lshlrev_b64 v[2:3], 12, v[2:3]
	v_lshlrev_b32_e32 v12, 4, v0
	v_lshl_add_u64 v[2:3], s[4:5], 0, v[2:3]
	v_lshl_add_u64 v[2:3], v[2:3], 0, v[12:13]
	s_waitcnt lgkmcnt(0)
	v_lshl_add_u64 v[2:3], s[10:11], 0, v[2:3]
	s_mov_b64 s[0:1], 0xc00
	v_lshl_add_u64 v[0:1], s[8:9], 0, v[12:13]
	v_lshlrev_b32_e32 v5, 2, v5
	v_lshlrev_b32_e32 v6, 2, v6
	v_lshlrev_b32_e32 v7, 2, v7
	v_lshlrev_b32_e32 v8, 2, v8
	v_lshlrev_b32_e32 v9, 2, v9
	v_lshl_add_u64 v[2:3], v[2:3], 0, s[0:1]
	v_mov_b32_e32 v11, 0x358637bd
	s_mov_b32 s4, 0xf800000
	v_mov_b32_e32 v12, 0x260
	s_movk_i32 s5, 0x7fff
	global_load_dwordx4 v[50:53], v[0:1], off
	global_load_dwordx4 v[54:57], v[0:1], off offset:1024
	global_load_dwordx4 v[58:61], v[0:1], off offset:2048
	global_load_dwordx4 v[62:65], v[0:1], off offset:3072
	s_waitcnt vmcnt(0)
.LBB0_2131:
	global_load_dwordx4 v[14:17], v[2:3], off offset:-3072
	global_load_dwordx4 v[18:21], v[2:3], off offset:-2048
	global_load_dwordx4 v[22:25], v[2:3], off
	global_load_dwordx4 v[26:29], v[2:3], off offset:-1024
	v_add_u32_e32 v4, s90, v4
	s_waitcnt vmcnt(3)
	v_pk_mul_f32 v[34:35], v[16:17], v[16:17]
	v_pk_mul_f32 v[36:37], v[14:15], v[14:15]
	s_waitcnt vmcnt(2)
	v_pk_mul_f32 v[38:39], v[20:21], v[20:21]
	v_pk_mul_f32 v[40:41], v[18:19], v[18:19]
	v_pk_mov_b32 v[46:47], v[36:37], v[34:35] op_sel:[1,0]
	v_mov_b32_e32 v37, v35
	v_pk_mov_b32 v[34:35], v[40:41], v[38:39] op_sel:[1,0]
	v_mov_b32_e32 v41, v39
	s_waitcnt vmcnt(1)
	v_mul_f32_e32 v45, v23, v23
	s_waitcnt vmcnt(0)
	v_mul_f32_e32 v42, v27, v27
	v_mul_f32_e32 v44, v29, v29
	v_pk_add_f32 v[36:37], v[46:47], v[36:37]
	v_pk_add_f32 v[34:35], v[34:35], v[40:41]
	v_mul_f32_e32 v13, v22, v22
	v_mul_f32_e32 v48, v24, v24
	v_mul_f32_e32 v49, v25, v25
	v_pk_fma_f32 v[38:39], v[26:27], v[26:27], v[42:43] op_sel_hi:[1,1,0]
	v_pk_fma_f32 v[42:43], v[28:29], v[28:29], v[44:45] op_sel_hi:[1,1,0]
	v_pk_add_f32 v[36:37], v[36:37], v[36:37] op_sel:[0,1] op_sel_hi:[1,0]
	v_pk_add_f32 v[34:35], v[34:35], v[34:35] op_sel:[0,1] op_sel_hi:[1,0]
	v_mov_b32_e32 v39, v48
	v_mov_b32_e32 v43, v49
	v_mov_b32_e32 v37, v13
	v_mov_b32_e32 v35, v45
	v_pk_add_f32 v[38:39], v[38:39], v[42:43]
	v_pk_add_f32 v[34:35], v[36:37], v[34:35]
	s_nop 0
	v_pk_add_f32 v[34:35], v[34:35], v[38:39]
	s_nop 0
	v_add_f32_e32 v13, v34, v35
	ds_bpermute_b32 v34, v5, v13
	s_waitcnt lgkmcnt(0)
	v_add_f32_e32 v13, v13, v34
	ds_bpermute_b32 v34, v6, v13
	s_waitcnt lgkmcnt(0)
	v_add_f32_e32 v13, v13, v34
	ds_bpermute_b32 v34, v7, v13
	s_waitcnt lgkmcnt(0)
	v_add_f32_e32 v13, v13, v34
	ds_bpermute_b32 v34, v8, v13
	s_waitcnt lgkmcnt(0)
	v_add_f32_e32 v13, v13, v34
	ds_bpermute_b32 v34, v9, v13
	s_waitcnt lgkmcnt(0)
	v_add_f32_e32 v13, v13, v34
	ds_bpermute_b32 v34, v10, v13
	s_waitcnt lgkmcnt(0)
	v_add_f32_e32 v13, v13, v34
	v_fmamk_f32 v13, v13, 0x3a800000, v11
	v_mul_f32_e32 v34, 0x4f800000, v13
	v_cmp_gt_f32_e32 vcc, s4, v13
	s_nop 1
	v_cndmask_b32_e32 v13, v13, v34, vcc
	v_sqrt_f32_e32 v34, v13
	s_nop 0
	v_add_u32_e32 v35, -1, v34
	v_add_u32_e32 v36, 1, v34
	v_fma_f32 v37, -v35, v34, v13
	v_fma_f32 v38, -v36, v34, v13
	v_cmp_ge_f32_e64 s[0:1], 0, v37
	s_nop 1
	v_cndmask_b32_e64 v34, v34, v35, s[0:1]
	v_cmp_lt_f32_e64 s[0:1], 0, v38
	s_nop 1
	v_cndmask_b32_e64 v34, v34, v36, s[0:1]
	v_mul_f32_e32 v35, 0x37800000, v34
	v_cndmask_b32_e32 v34, v34, v35, vcc
	v_cmp_class_f32_e32 vcc, v13, v12
	s_nop 1
	v_cndmask_b32_e32 v13, v34, v13, vcc
	v_div_scale_f32 v34, s[0:1], v13, v13, 1.0
	v_rcp_f32_e32 v35, v34
	v_div_scale_f32 v36, vcc, 1.0, v13, 1.0
	v_fma_f32 v37, -v34, v35, 1.0
	v_fmac_f32_e32 v35, v37, v35
	v_mul_f32_e32 v37, v36, v35
	v_fma_f32 v38, -v34, v37, v36
	v_fmac_f32_e32 v37, v38, v35
	v_fma_f32 v34, -v34, v37, v36
	v_div_fmas_f32 v34, v34, v35, v37
	v_div_fixup_f32 v34, v34, v13, 1.0
	v_pk_mul_f32 v[14:15], v[14:15], v[34:35] op_sel_hi:[1,0]
	v_pk_mul_f32 v[16:17], v[16:17], v[34:35] op_sel_hi:[1,0]
	v_pk_mul_f32 v[14:15], v[50:51], v[14:15]
	v_pk_mul_f32 v[16:17], v[52:53], v[16:17]
	global_store_dwordx4 v[2:3], v[14:17], off offset:-3072
	v_pk_mul_f32 v[20:21], v[20:21], v[34:35] op_sel_hi:[1,0]
	v_pk_mul_f32 v[18:19], v[18:19], v[34:35] op_sel_hi:[1,0]
	v_cmp_lt_i32_e32 vcc, s5, v4
	s_or_b64 s[2:3], vcc, s[2:3]
	v_pk_mul_f32 v[14:15], v[54:55], v[18:19]
	v_pk_mul_f32 v[16:17], v[56:57], v[20:21]
	global_store_dwordx4 v[2:3], v[14:17], off offset:-2048
	v_pk_mul_f32 v[18:19], v[28:29], v[34:35] op_sel_hi:[1,0]
	v_pk_mul_f32 v[20:21], v[26:27], v[34:35] op_sel_hi:[1,0]
	v_pk_mul_f32 v[16:17], v[60:61], v[18:19]
	v_pk_mul_f32 v[14:15], v[58:59], v[20:21]
	global_store_dwordx4 v[2:3], v[14:17], off offset:-1024
	v_pk_mul_f32 v[18:19], v[24:25], v[34:35] op_sel_hi:[1,0]
	v_pk_mul_f32 v[20:21], v[22:23], v[34:35] op_sel_hi:[1,0]
	v_pk_mul_f32 v[16:17], v[64:65], v[18:19]
	v_pk_mul_f32 v[14:15], v[62:63], v[20:21]
	global_store_dwordx4 v[2:3], v[14:17], off
	v_lshl_add_u64 v[2:3], v[2:3], 0, s[86:87]
	s_andn2_b64 exec, exec, s[2:3]
	s_cbranch_execnz .LBB0_2131
